# mLSTM gate pre-pass stage 1: DPP row scans + up-front gate loads; grid barrier code relocated mid-kernel
# baseline (speedup 1.0000x reference)
.Lfar_23:
	s_branch .LBB0_23
.LBB0_576:
	s_waitcnt vmcnt(0)
	s_waitcnt vmcnt(0) lgkmcnt(0)
	s_barrier
	s_mov_b64 s[6:7], exec
	v_readlane_b32 s0, v253, 53
	v_readlane_b32 s1, v253, 54
	s_and_b64 s[0:1], s[6:7], s[0:1]
	s_mov_b64 exec, s[0:1]
	s_cbranch_execz .LBB0_22
	v_readlane_b32 s0, v253, 51
	s_waitcnt vmcnt(0) expcnt(0) lgkmcnt(0)
	s_nop 0
	v_mov_b32_e32 v0, s0
	ds_read_b32 v3, v0
	v_readlane_b32 s0, v253, 52
	s_waitcnt lgkmcnt(0)
	v_cmp_ne_u32_e32 vcc, 0, v3
	v_mov_b32_e32 v0, s0
	ds_read_b32 v2, v0
	s_cbranch_vccnz .LBB0_592
	s_mov_b32 s0, 1
	s_branch .LBB0_580

.Lxb_done:
	buffer_inv sc1
	s_waitcnt vmcnt(0)
	s_branch .LBB0_22
.Lfar_end:
	s_branch .LBB0_623

.LBB0_212:
	s_lshr_b32 s0, s7, 3
	v_writelane_b32 v255, s0, 3
	s_bfe_u32 s0, s7, 0x10002
	s_bfe_u32 s21, s7, 0x30003
	v_mov_b32_e32 v0, 0x28000
	s_cmp_eq_u32 s0, 0
	v_mad_i64_i32 v[2:3], s[22:23], s7, v0, v[64:65]
	s_cselect_b64 s[92:93], -1, 0
	s_lshl_b32 s1, s7, 7
	s_and_b32 s34, s1, 0xffffe000
	s_lshl_b32 s0, s0, 5
	v_readlane_b32 s22, v254, 50
	v_readlane_b32 s23, v254, 51
	s_add_u32 s0, s22, s0
	s_addc_u32 s1, s23, 0
	s_lshl_b32 s20, s21, 2
	v_cndmask_b32_e64 v0, v87, v81, s[92:93]
	s_add_u32 s30, s0, s20
	s_mul_hi_i32 s29, s7, 0x28000
	s_mul_i32 s28, s7, 0x28000
	s_mov_b32 s4, 0
	v_or_b32_e32 v0, s34, v0
	s_addc_u32 s31, s1, 0
	v_readlane_b32 s22, v255, 0
	v_readlane_b32 s23, v255, 1
	s_waitcnt vmcnt(0)
	s_barrier
	s_and_b64 s[94:95], s[92:93], exec
	s_cselect_b32 s0, s22, s23
	v_add_u32_e32 v12, s0, v0
	v_ashrrev_i32_e32 v13, 31, v12
	v_lshlrev_b64 v[12:13], 7, v[12:13]
	v_lshl_add_u64 v[18:19], s[30:31], 0, v[12:13]
	s_mov_b32 s22, 0xffff0000
	s_cselect_b32 s22, 0x10000, s22
	s_cselect_b32 s23, 0, -1
	s_mov_b32 s30, 0x2800
	s_mov_b32 s31, 0
	s_mov_b32 s0, 0x3f317217
	s_mov_b32 s1, 0x7f800000
	v_add_co_u32_e32 v2, vcc, 0xffffd400, v2
	s_nop 1
	v_addc_co_u32_e32 v3, vcc, -1, v3, vcc
	global_load_dword v216, v[18:19], off
	global_load_dword v217, v[18:19], off offset:64
	v_lshl_add_u64 v[18:19], v[18:19], 0, s[22:23]
	global_load_dword v218, v[18:19], off
	global_load_dword v219, v[18:19], off offset:64
	v_lshl_add_u64 v[18:19], v[18:19], 0, s[22:23]
	global_load_dword v220, v[18:19], off
	global_load_dword v221, v[18:19], off offset:64
	v_lshl_add_u64 v[18:19], v[18:19], 0, s[22:23]
	global_load_dword v230, v[18:19], off
	global_load_dword v231, v[18:19], off offset:64
	v_lshl_add_u64 v[18:19], v[18:19], 0, s[22:23]
	global_load_dword v232, v[18:19], off
	global_load_dword v233, v[18:19], off offset:64
	v_lshl_add_u64 v[18:19], v[18:19], 0, s[22:23]
	global_load_dword v234, v[18:19], off
	global_load_dword v235, v[18:19], off offset:64
	v_lshl_add_u64 v[18:19], v[18:19], 0, s[22:23]
	global_load_dword v236, v[18:19], off
	global_load_dword v237, v[18:19], off offset:64
	v_lshl_add_u64 v[18:19], v[18:19], 0, s[22:23]
	global_load_dword v238, v[18:19], off
	global_load_dword v239, v[18:19], off offset:64
	v_lshl_add_u64 v[18:19], v[18:19], 0, s[22:23]
	global_load_dword v240, v[18:19], off
	global_load_dword v241, v[18:19], off offset:64
	v_lshl_add_u64 v[18:19], v[18:19], 0, s[22:23]
	global_load_dword v242, v[18:19], off
	global_load_dword v243, v[18:19], off offset:64
	v_lshl_add_u64 v[18:19], v[18:19], 0, s[22:23]
	global_load_dword v244, v[18:19], off
	global_load_dword v245, v[18:19], off offset:64
	v_lshl_add_u64 v[18:19], v[18:19], 0, s[22:23]
	global_load_dword v246, v[18:19], off
	global_load_dword v247, v[18:19], off offset:64
	v_lshl_add_u64 v[18:19], v[18:19], 0, s[22:23]
	global_load_dword v248, v[18:19], off
	global_load_dword v249, v[18:19], off offset:64
	v_lshl_add_u64 v[18:19], v[18:19], 0, s[22:23]
	global_load_dword v250, v[18:19], off
	global_load_dword v251, v[18:19], off offset:64
	v_lshl_add_u64 v[18:19], v[18:19], 0, s[22:23]
	global_load_dword v197, v[18:19], off
	global_load_dword v198, v[18:19], off offset:64
	v_lshl_add_u64 v[18:19], v[18:19], 0, s[22:23]
	global_load_dword v199, v[18:19], off
	global_load_dword v200, v[18:19], off offset:64
	v_lshl_add_u64 v[18:19], v[18:19], 0, s[22:23]
	s_waitcnt vmcnt(30)
	v_mul_f32_e32 v12, 0xbfb8aa3b, v217
	v_exp_f32_e32 v12, v12
	s_nop 0
	v_add_f32_e32 v12, 1.0, v12
	v_cmp_gt_f32_e32 vcc, s39, v12
	s_nop 1
	v_cndmask_b32_e64 v13, 0, 32, vcc
	v_ldexp_f32 v12, v12, v13
	v_log_f32_e32 v12, v12
	v_cndmask_b32_e32 v13, 0, v213, vcc
	v_mul_f32_e32 v14, 0x3f317217, v12
	v_fma_f32 v14, v12, s0, -v14
	v_fmac_f32_e32 v14, 0x3377d1cf, v12
	v_fmac_f32_e32 v14, 0x3f317217, v12
	v_cmp_lt_f32_e64 vcc, |v12|, s1
	s_nop 1
	v_cndmask_b32_e32 v12, v12, v14, vcc
	v_sub_f32_e32 v12, v12, v13
	v_xor_b32_e32 v12, 0x80000000, v12
	s_nop 1
	v_add_f32_dpp v12, v12, v12 row_shr:1 row_mask:0xf bank_mask:0xf bound_ctrl:0
	s_nop 1
	v_add_f32_dpp v12, v12, v12 row_shr:2 row_mask:0xf bank_mask:0xf bound_ctrl:0
	s_nop 1
	v_add_f32_dpp v12, v12, v12 row_shr:4 row_mask:0xf bank_mask:0xf bound_ctrl:0
	s_nop 1
	v_add_f32_dpp v12, v12, v12 row_shr:8 row_mask:0xf bank_mask:0xf bound_ctrl:0
	s_nop 1
	v_add_f32_dpp v12, v12, v12 row_bcast:15 row_mask:0xa bank_mask:0xf
	s_nop 1
	v_add_f32_dpp v12, v12, v12 row_bcast:31 row_mask:0xc bank_mask:0xf
	v_sub_f32_e32 v15, v216, v12
	s_nop 0
	v_readlane_b32 s4, v12, 63
	v_mov_b32_e32 v14, v15
	s_nop 1
	v_sub_f32_e32 v16, s4, v12
	v_add_f32_e32 v16, v216, v16
	global_store_dword v[2:3], v12, off
	global_store_dword v[2:3], v15, off offset:1024
	v_max_f32_dpp v14, v14, v14 row_shr:1 row_mask:0xf bank_mask:0xf
	v_max_f32_dpp v16, v16, v16 row_shr:1 row_mask:0xf bank_mask:0xf
	s_nop 0
	v_max_f32_dpp v14, v14, v14 row_shr:2 row_mask:0xf bank_mask:0xf
	v_max_f32_dpp v16, v16, v16 row_shr:2 row_mask:0xf bank_mask:0xf
	s_nop 0
	v_max_f32_dpp v14, v14, v14 row_shr:4 row_mask:0xf bank_mask:0xf
	v_max_f32_dpp v16, v16, v16 row_shr:4 row_mask:0xf bank_mask:0xf
	s_nop 0
	v_max_f32_dpp v14, v14, v14 row_shr:8 row_mask:0xf bank_mask:0xf
	v_max_f32_dpp v16, v16, v16 row_shr:8 row_mask:0xf bank_mask:0xf
	s_nop 0
	v_max_f32_dpp v14, v14, v14 row_bcast:15 row_mask:0xa bank_mask:0xf
	v_max_f32_dpp v16, v16, v16 row_bcast:15 row_mask:0xa bank_mask:0xf
	s_nop 0
	v_max_f32_dpp v14, v14, v14 row_bcast:31 row_mask:0xc bank_mask:0xf
	v_max_f32_dpp v16, v16, v16 row_bcast:31 row_mask:0xc bank_mask:0xf
	s_nop 0
	v_writelane_b32 v206, s4, 0
	v_readlane_b32 s20, v16, 63
	global_store_dword v[2:3], v14, off offset:256
	v_lshl_add_u64 v[2:3], v[2:3], 0, s[30:31]
	v_writelane_b32 v207, s20, 0
	s_waitcnt vmcnt(31)
	v_mul_f32_e32 v12, 0xbfb8aa3b, v219
	v_exp_f32_e32 v12, v12
	s_nop 0
	v_add_f32_e32 v12, 1.0, v12
	v_cmp_gt_f32_e32 vcc, s39, v12
	s_nop 1
	v_cndmask_b32_e64 v13, 0, 32, vcc
	v_ldexp_f32 v12, v12, v13
	v_log_f32_e32 v12, v12
	v_cndmask_b32_e32 v13, 0, v213, vcc
	v_mul_f32_e32 v14, 0x3f317217, v12
	v_fma_f32 v14, v12, s0, -v14
	v_fmac_f32_e32 v14, 0x3377d1cf, v12
	v_fmac_f32_e32 v14, 0x3f317217, v12
	v_cmp_lt_f32_e64 vcc, |v12|, s1
	s_nop 1
	v_cndmask_b32_e32 v12, v12, v14, vcc
	v_sub_f32_e32 v12, v12, v13
	v_xor_b32_e32 v12, 0x80000000, v12
	s_nop 1
	v_add_f32_dpp v12, v12, v12 row_shr:1 row_mask:0xf bank_mask:0xf bound_ctrl:0
	s_nop 1
	v_add_f32_dpp v12, v12, v12 row_shr:2 row_mask:0xf bank_mask:0xf bound_ctrl:0
	s_nop 1
	v_add_f32_dpp v12, v12, v12 row_shr:4 row_mask:0xf bank_mask:0xf bound_ctrl:0
	s_nop 1
	v_add_f32_dpp v12, v12, v12 row_shr:8 row_mask:0xf bank_mask:0xf bound_ctrl:0
	s_nop 1
	v_add_f32_dpp v12, v12, v12 row_bcast:15 row_mask:0xa bank_mask:0xf
	s_nop 1
	v_add_f32_dpp v12, v12, v12 row_bcast:31 row_mask:0xc bank_mask:0xf
	v_sub_f32_e32 v15, v218, v12
	s_nop 0
	v_readlane_b32 s4, v12, 63
	v_mov_b32_e32 v14, v15
	s_nop 1
	v_sub_f32_e32 v16, s4, v12
	v_add_f32_e32 v16, v218, v16
	global_store_dword v[2:3], v12, off
	global_store_dword v[2:3], v15, off offset:1024
	v_max_f32_dpp v14, v14, v14 row_shr:1 row_mask:0xf bank_mask:0xf
	v_max_f32_dpp v16, v16, v16 row_shr:1 row_mask:0xf bank_mask:0xf
	s_nop 0
	v_max_f32_dpp v14, v14, v14 row_shr:2 row_mask:0xf bank_mask:0xf
	v_max_f32_dpp v16, v16, v16 row_shr:2 row_mask:0xf bank_mask:0xf
	s_nop 0
	v_max_f32_dpp v14, v14, v14 row_shr:4 row_mask:0xf bank_mask:0xf
	v_max_f32_dpp v16, v16, v16 row_shr:4 row_mask:0xf bank_mask:0xf
	s_nop 0
	v_max_f32_dpp v14, v14, v14 row_shr:8 row_mask:0xf bank_mask:0xf
	v_max_f32_dpp v16, v16, v16 row_shr:8 row_mask:0xf bank_mask:0xf
	s_nop 0
	v_max_f32_dpp v14, v14, v14 row_bcast:15 row_mask:0xa bank_mask:0xf
	v_max_f32_dpp v16, v16, v16 row_bcast:15 row_mask:0xa bank_mask:0xf
	s_nop 0
	v_max_f32_dpp v14, v14, v14 row_bcast:31 row_mask:0xc bank_mask:0xf
	v_max_f32_dpp v16, v16, v16 row_bcast:31 row_mask:0xc bank_mask:0xf
	s_nop 0
	v_writelane_b32 v206, s4, 1
	v_readlane_b32 s20, v16, 63
	global_store_dword v[2:3], v14, off offset:256
	v_lshl_add_u64 v[2:3], v[2:3], 0, s[30:31]
	v_writelane_b32 v207, s20, 1
	s_waitcnt vmcnt(32)
	v_mul_f32_e32 v12, 0xbfb8aa3b, v221
	v_exp_f32_e32 v12, v12
	s_nop 0
	v_add_f32_e32 v12, 1.0, v12
	v_cmp_gt_f32_e32 vcc, s39, v12
	s_nop 1
	v_cndmask_b32_e64 v13, 0, 32, vcc
	v_ldexp_f32 v12, v12, v13
	v_log_f32_e32 v12, v12
	v_cndmask_b32_e32 v13, 0, v213, vcc
	v_mul_f32_e32 v14, 0x3f317217, v12
	v_fma_f32 v14, v12, s0, -v14
	v_fmac_f32_e32 v14, 0x3377d1cf, v12
	v_fmac_f32_e32 v14, 0x3f317217, v12
	v_cmp_lt_f32_e64 vcc, |v12|, s1
	s_nop 1
	v_cndmask_b32_e32 v12, v12, v14, vcc
	v_sub_f32_e32 v12, v12, v13
	v_xor_b32_e32 v12, 0x80000000, v12
	s_nop 1
	v_add_f32_dpp v12, v12, v12 row_shr:1 row_mask:0xf bank_mask:0xf bound_ctrl:0
	s_nop 1
	v_add_f32_dpp v12, v12, v12 row_shr:2 row_mask:0xf bank_mask:0xf bound_ctrl:0
	s_nop 1
	v_add_f32_dpp v12, v12, v12 row_shr:4 row_mask:0xf bank_mask:0xf bound_ctrl:0
	s_nop 1
	v_add_f32_dpp v12, v12, v12 row_shr:8 row_mask:0xf bank_mask:0xf bound_ctrl:0
	s_nop 1
	v_add_f32_dpp v12, v12, v12 row_bcast:15 row_mask:0xa bank_mask:0xf
	s_nop 1
	v_add_f32_dpp v12, v12, v12 row_bcast:31 row_mask:0xc bank_mask:0xf
	v_sub_f32_e32 v15, v220, v12
	s_nop 0
	v_readlane_b32 s4, v12, 63
	v_mov_b32_e32 v14, v15
	s_nop 1
	v_sub_f32_e32 v16, s4, v12
	v_add_f32_e32 v16, v220, v16
	global_store_dword v[2:3], v12, off
	global_store_dword v[2:3], v15, off offset:1024
	v_max_f32_dpp v14, v14, v14 row_shr:1 row_mask:0xf bank_mask:0xf
	v_max_f32_dpp v16, v16, v16 row_shr:1 row_mask:0xf bank_mask:0xf
	s_nop 0
	v_max_f32_dpp v14, v14, v14 row_shr:2 row_mask:0xf bank_mask:0xf
	v_max_f32_dpp v16, v16, v16 row_shr:2 row_mask:0xf bank_mask:0xf
	s_nop 0
	v_max_f32_dpp v14, v14, v14 row_shr:4 row_mask:0xf bank_mask:0xf
	v_max_f32_dpp v16, v16, v16 row_shr:4 row_mask:0xf bank_mask:0xf
	s_nop 0
	v_max_f32_dpp v14, v14, v14 row_shr:8 row_mask:0xf bank_mask:0xf
	v_max_f32_dpp v16, v16, v16 row_shr:8 row_mask:0xf bank_mask:0xf
	s_nop 0
	v_max_f32_dpp v14, v14, v14 row_bcast:15 row_mask:0xa bank_mask:0xf
	v_max_f32_dpp v16, v16, v16 row_bcast:15 row_mask:0xa bank_mask:0xf
	s_nop 0
	v_max_f32_dpp v14, v14, v14 row_bcast:31 row_mask:0xc bank_mask:0xf
	v_max_f32_dpp v16, v16, v16 row_bcast:31 row_mask:0xc bank_mask:0xf
	s_nop 0
	v_writelane_b32 v206, s4, 2
	v_readlane_b32 s20, v16, 63
	global_store_dword v[2:3], v14, off offset:256
	v_lshl_add_u64 v[2:3], v[2:3], 0, s[30:31]
	v_writelane_b32 v207, s20, 2
	s_waitcnt vmcnt(33)
	v_mul_f32_e32 v12, 0xbfb8aa3b, v231
	v_exp_f32_e32 v12, v12
	s_nop 0
	v_add_f32_e32 v12, 1.0, v12
	v_cmp_gt_f32_e32 vcc, s39, v12
	s_nop 1
	v_cndmask_b32_e64 v13, 0, 32, vcc
	v_ldexp_f32 v12, v12, v13
	v_log_f32_e32 v12, v12
	v_cndmask_b32_e32 v13, 0, v213, vcc
	v_mul_f32_e32 v14, 0x3f317217, v12
	v_fma_f32 v14, v12, s0, -v14
	v_fmac_f32_e32 v14, 0x3377d1cf, v12
	v_fmac_f32_e32 v14, 0x3f317217, v12
	v_cmp_lt_f32_e64 vcc, |v12|, s1
	s_nop 1
	v_cndmask_b32_e32 v12, v12, v14, vcc
	v_sub_f32_e32 v12, v12, v13
	v_xor_b32_e32 v12, 0x80000000, v12
	s_nop 1
	v_add_f32_dpp v12, v12, v12 row_shr:1 row_mask:0xf bank_mask:0xf bound_ctrl:0
	s_nop 1
	v_add_f32_dpp v12, v12, v12 row_shr:2 row_mask:0xf bank_mask:0xf bound_ctrl:0
	s_nop 1
	v_add_f32_dpp v12, v12, v12 row_shr:4 row_mask:0xf bank_mask:0xf bound_ctrl:0
	s_nop 1
	v_add_f32_dpp v12, v12, v12 row_shr:8 row_mask:0xf bank_mask:0xf bound_ctrl:0
	s_nop 1
	v_add_f32_dpp v12, v12, v12 row_bcast:15 row_mask:0xa bank_mask:0xf
	s_nop 1
	v_add_f32_dpp v12, v12, v12 row_bcast:31 row_mask:0xc bank_mask:0xf
	v_sub_f32_e32 v15, v230, v12
	s_nop 0
	v_readlane_b32 s4, v12, 63
	v_mov_b32_e32 v14, v15
	s_nop 1
	v_sub_f32_e32 v16, s4, v12
	v_add_f32_e32 v16, v230, v16
	global_store_dword v[2:3], v12, off
	global_store_dword v[2:3], v15, off offset:1024
	v_max_f32_dpp v14, v14, v14 row_shr:1 row_mask:0xf bank_mask:0xf
	v_max_f32_dpp v16, v16, v16 row_shr:1 row_mask:0xf bank_mask:0xf
	s_nop 0
	v_max_f32_dpp v14, v14, v14 row_shr:2 row_mask:0xf bank_mask:0xf
	v_max_f32_dpp v16, v16, v16 row_shr:2 row_mask:0xf bank_mask:0xf
	s_nop 0
	v_max_f32_dpp v14, v14, v14 row_shr:4 row_mask:0xf bank_mask:0xf
	v_max_f32_dpp v16, v16, v16 row_shr:4 row_mask:0xf bank_mask:0xf
	s_nop 0
	v_max_f32_dpp v14, v14, v14 row_shr:8 row_mask:0xf bank_mask:0xf
	v_max_f32_dpp v16, v16, v16 row_shr:8 row_mask:0xf bank_mask:0xf
	s_nop 0
	v_max_f32_dpp v14, v14, v14 row_bcast:15 row_mask:0xa bank_mask:0xf
	v_max_f32_dpp v16, v16, v16 row_bcast:15 row_mask:0xa bank_mask:0xf
	s_nop 0
	v_max_f32_dpp v14, v14, v14 row_bcast:31 row_mask:0xc bank_mask:0xf
	v_max_f32_dpp v16, v16, v16 row_bcast:31 row_mask:0xc bank_mask:0xf
	s_nop 0
	v_writelane_b32 v206, s4, 3
	v_readlane_b32 s20, v16, 63
	global_store_dword v[2:3], v14, off offset:256
	v_lshl_add_u64 v[2:3], v[2:3], 0, s[30:31]
	v_writelane_b32 v207, s20, 3
	s_waitcnt vmcnt(34)
	v_mul_f32_e32 v12, 0xbfb8aa3b, v233
	v_exp_f32_e32 v12, v12
	s_nop 0
	v_add_f32_e32 v12, 1.0, v12
	v_cmp_gt_f32_e32 vcc, s39, v12
	s_nop 1
	v_cndmask_b32_e64 v13, 0, 32, vcc
	v_ldexp_f32 v12, v12, v13
	v_log_f32_e32 v12, v12
	v_cndmask_b32_e32 v13, 0, v213, vcc
	v_mul_f32_e32 v14, 0x3f317217, v12
	v_fma_f32 v14, v12, s0, -v14
	v_fmac_f32_e32 v14, 0x3377d1cf, v12
	v_fmac_f32_e32 v14, 0x3f317217, v12
	v_cmp_lt_f32_e64 vcc, |v12|, s1
	s_nop 1
	v_cndmask_b32_e32 v12, v12, v14, vcc
	v_sub_f32_e32 v12, v12, v13
	v_xor_b32_e32 v12, 0x80000000, v12
	s_nop 1
	v_add_f32_dpp v12, v12, v12 row_shr:1 row_mask:0xf bank_mask:0xf bound_ctrl:0
	s_nop 1
	v_add_f32_dpp v12, v12, v12 row_shr:2 row_mask:0xf bank_mask:0xf bound_ctrl:0
	s_nop 1
	v_add_f32_dpp v12, v12, v12 row_shr:4 row_mask:0xf bank_mask:0xf bound_ctrl:0
	s_nop 1
	v_add_f32_dpp v12, v12, v12 row_shr:8 row_mask:0xf bank_mask:0xf bound_ctrl:0
	s_nop 1
	v_add_f32_dpp v12, v12, v12 row_bcast:15 row_mask:0xa bank_mask:0xf
	s_nop 1
	v_add_f32_dpp v12, v12, v12 row_bcast:31 row_mask:0xc bank_mask:0xf
	v_sub_f32_e32 v15, v232, v12
	s_nop 0
	v_readlane_b32 s4, v12, 63
	v_mov_b32_e32 v14, v15
	s_nop 1
	v_sub_f32_e32 v16, s4, v12
	v_add_f32_e32 v16, v232, v16
	global_store_dword v[2:3], v12, off
	global_store_dword v[2:3], v15, off offset:1024
	v_max_f32_dpp v14, v14, v14 row_shr:1 row_mask:0xf bank_mask:0xf
	v_max_f32_dpp v16, v16, v16 row_shr:1 row_mask:0xf bank_mask:0xf
	s_nop 0
	v_max_f32_dpp v14, v14, v14 row_shr:2 row_mask:0xf bank_mask:0xf
	v_max_f32_dpp v16, v16, v16 row_shr:2 row_mask:0xf bank_mask:0xf
	s_nop 0
	v_max_f32_dpp v14, v14, v14 row_shr:4 row_mask:0xf bank_mask:0xf
	v_max_f32_dpp v16, v16, v16 row_shr:4 row_mask:0xf bank_mask:0xf
	s_nop 0
	v_max_f32_dpp v14, v14, v14 row_shr:8 row_mask:0xf bank_mask:0xf
	v_max_f32_dpp v16, v16, v16 row_shr:8 row_mask:0xf bank_mask:0xf
	s_nop 0
	v_max_f32_dpp v14, v14, v14 row_bcast:15 row_mask:0xa bank_mask:0xf
	v_max_f32_dpp v16, v16, v16 row_bcast:15 row_mask:0xa bank_mask:0xf
	s_nop 0
	v_max_f32_dpp v14, v14, v14 row_bcast:31 row_mask:0xc bank_mask:0xf
	v_max_f32_dpp v16, v16, v16 row_bcast:31 row_mask:0xc bank_mask:0xf
	s_nop 0
	v_writelane_b32 v206, s4, 4
	v_readlane_b32 s20, v16, 63
	global_store_dword v[2:3], v14, off offset:256
	v_lshl_add_u64 v[2:3], v[2:3], 0, s[30:31]
	v_writelane_b32 v207, s20, 4
	s_waitcnt vmcnt(35)
	v_mul_f32_e32 v12, 0xbfb8aa3b, v235
	v_exp_f32_e32 v12, v12
	s_nop 0
	v_add_f32_e32 v12, 1.0, v12
	v_cmp_gt_f32_e32 vcc, s39, v12
	s_nop 1
	v_cndmask_b32_e64 v13, 0, 32, vcc
	v_ldexp_f32 v12, v12, v13
	v_log_f32_e32 v12, v12
	v_cndmask_b32_e32 v13, 0, v213, vcc
	v_mul_f32_e32 v14, 0x3f317217, v12
	v_fma_f32 v14, v12, s0, -v14
	v_fmac_f32_e32 v14, 0x3377d1cf, v12
	v_fmac_f32_e32 v14, 0x3f317217, v12
	v_cmp_lt_f32_e64 vcc, |v12|, s1
	s_nop 1
	v_cndmask_b32_e32 v12, v12, v14, vcc
	v_sub_f32_e32 v12, v12, v13
	v_xor_b32_e32 v12, 0x80000000, v12
	s_nop 1
	v_add_f32_dpp v12, v12, v12 row_shr:1 row_mask:0xf bank_mask:0xf bound_ctrl:0
	s_nop 1
	v_add_f32_dpp v12, v12, v12 row_shr:2 row_mask:0xf bank_mask:0xf bound_ctrl:0
	s_nop 1
	v_add_f32_dpp v12, v12, v12 row_shr:4 row_mask:0xf bank_mask:0xf bound_ctrl:0
	s_nop 1
	v_add_f32_dpp v12, v12, v12 row_shr:8 row_mask:0xf bank_mask:0xf bound_ctrl:0
	s_nop 1
	v_add_f32_dpp v12, v12, v12 row_bcast:15 row_mask:0xa bank_mask:0xf
	s_nop 1
	v_add_f32_dpp v12, v12, v12 row_bcast:31 row_mask:0xc bank_mask:0xf
	v_sub_f32_e32 v15, v234, v12
	s_nop 0
	v_readlane_b32 s4, v12, 63
	v_mov_b32_e32 v14, v15
	s_nop 1
	v_sub_f32_e32 v16, s4, v12
	v_add_f32_e32 v16, v234, v16
	global_store_dword v[2:3], v12, off
	global_store_dword v[2:3], v15, off offset:1024
	v_max_f32_dpp v14, v14, v14 row_shr:1 row_mask:0xf bank_mask:0xf
	v_max_f32_dpp v16, v16, v16 row_shr:1 row_mask:0xf bank_mask:0xf
	s_nop 0
	v_max_f32_dpp v14, v14, v14 row_shr:2 row_mask:0xf bank_mask:0xf
	v_max_f32_dpp v16, v16, v16 row_shr:2 row_mask:0xf bank_mask:0xf
	s_nop 0
	v_max_f32_dpp v14, v14, v14 row_shr:4 row_mask:0xf bank_mask:0xf
	v_max_f32_dpp v16, v16, v16 row_shr:4 row_mask:0xf bank_mask:0xf
	s_nop 0
	v_max_f32_dpp v14, v14, v14 row_shr:8 row_mask:0xf bank_mask:0xf
	v_max_f32_dpp v16, v16, v16 row_shr:8 row_mask:0xf bank_mask:0xf
	s_nop 0
	v_max_f32_dpp v14, v14, v14 row_bcast:15 row_mask:0xa bank_mask:0xf
	v_max_f32_dpp v16, v16, v16 row_bcast:15 row_mask:0xa bank_mask:0xf
	s_nop 0
	v_max_f32_dpp v14, v14, v14 row_bcast:31 row_mask:0xc bank_mask:0xf
	v_max_f32_dpp v16, v16, v16 row_bcast:31 row_mask:0xc bank_mask:0xf
	s_nop 0
	v_writelane_b32 v206, s4, 5
	v_readlane_b32 s20, v16, 63
	global_store_dword v[2:3], v14, off offset:256
	v_lshl_add_u64 v[2:3], v[2:3], 0, s[30:31]
	v_writelane_b32 v207, s20, 5
	s_waitcnt vmcnt(36)
	v_mul_f32_e32 v12, 0xbfb8aa3b, v237
	v_exp_f32_e32 v12, v12
	s_nop 0
	v_add_f32_e32 v12, 1.0, v12
	v_cmp_gt_f32_e32 vcc, s39, v12
	s_nop 1
	v_cndmask_b32_e64 v13, 0, 32, vcc
	v_ldexp_f32 v12, v12, v13
	v_log_f32_e32 v12, v12
	v_cndmask_b32_e32 v13, 0, v213, vcc
	v_mul_f32_e32 v14, 0x3f317217, v12
	v_fma_f32 v14, v12, s0, -v14
	v_fmac_f32_e32 v14, 0x3377d1cf, v12
	v_fmac_f32_e32 v14, 0x3f317217, v12
	v_cmp_lt_f32_e64 vcc, |v12|, s1
	s_nop 1
	v_cndmask_b32_e32 v12, v12, v14, vcc
	v_sub_f32_e32 v12, v12, v13
	v_xor_b32_e32 v12, 0x80000000, v12
	s_nop 1
	v_add_f32_dpp v12, v12, v12 row_shr:1 row_mask:0xf bank_mask:0xf bound_ctrl:0
	s_nop 1
	v_add_f32_dpp v12, v12, v12 row_shr:2 row_mask:0xf bank_mask:0xf bound_ctrl:0
	s_nop 1
	v_add_f32_dpp v12, v12, v12 row_shr:4 row_mask:0xf bank_mask:0xf bound_ctrl:0
	s_nop 1
	v_add_f32_dpp v12, v12, v12 row_shr:8 row_mask:0xf bank_mask:0xf bound_ctrl:0
	s_nop 1
	v_add_f32_dpp v12, v12, v12 row_bcast:15 row_mask:0xa bank_mask:0xf
	s_nop 1
	v_add_f32_dpp v12, v12, v12 row_bcast:31 row_mask:0xc bank_mask:0xf
	v_sub_f32_e32 v15, v236, v12
	s_nop 0
	v_readlane_b32 s4, v12, 63
	v_mov_b32_e32 v14, v15
	s_nop 1
	v_sub_f32_e32 v16, s4, v12
	v_add_f32_e32 v16, v236, v16
	global_store_dword v[2:3], v12, off
	global_store_dword v[2:3], v15, off offset:1024
	v_max_f32_dpp v14, v14, v14 row_shr:1 row_mask:0xf bank_mask:0xf
	v_max_f32_dpp v16, v16, v16 row_shr:1 row_mask:0xf bank_mask:0xf
	s_nop 0
	v_max_f32_dpp v14, v14, v14 row_shr:2 row_mask:0xf bank_mask:0xf
	v_max_f32_dpp v16, v16, v16 row_shr:2 row_mask:0xf bank_mask:0xf
	s_nop 0
	v_max_f32_dpp v14, v14, v14 row_shr:4 row_mask:0xf bank_mask:0xf
	v_max_f32_dpp v16, v16, v16 row_shr:4 row_mask:0xf bank_mask:0xf
	s_nop 0
	v_max_f32_dpp v14, v14, v14 row_shr:8 row_mask:0xf bank_mask:0xf
	v_max_f32_dpp v16, v16, v16 row_shr:8 row_mask:0xf bank_mask:0xf
	s_nop 0
	v_max_f32_dpp v14, v14, v14 row_bcast:15 row_mask:0xa bank_mask:0xf
	v_max_f32_dpp v16, v16, v16 row_bcast:15 row_mask:0xa bank_mask:0xf
	s_nop 0
	v_max_f32_dpp v14, v14, v14 row_bcast:31 row_mask:0xc bank_mask:0xf
	v_max_f32_dpp v16, v16, v16 row_bcast:31 row_mask:0xc bank_mask:0xf
	s_nop 0
	v_writelane_b32 v206, s4, 6
	v_readlane_b32 s20, v16, 63
	global_store_dword v[2:3], v14, off offset:256
	v_lshl_add_u64 v[2:3], v[2:3], 0, s[30:31]
	v_writelane_b32 v207, s20, 6
	s_waitcnt vmcnt(37)
	v_mul_f32_e32 v12, 0xbfb8aa3b, v239
	v_exp_f32_e32 v12, v12
	s_nop 0
	v_add_f32_e32 v12, 1.0, v12
	v_cmp_gt_f32_e32 vcc, s39, v12
	s_nop 1
	v_cndmask_b32_e64 v13, 0, 32, vcc
	v_ldexp_f32 v12, v12, v13
	v_log_f32_e32 v12, v12
	v_cndmask_b32_e32 v13, 0, v213, vcc
	v_mul_f32_e32 v14, 0x3f317217, v12
	v_fma_f32 v14, v12, s0, -v14
	v_fmac_f32_e32 v14, 0x3377d1cf, v12
	v_fmac_f32_e32 v14, 0x3f317217, v12
	v_cmp_lt_f32_e64 vcc, |v12|, s1
	s_nop 1
	v_cndmask_b32_e32 v12, v12, v14, vcc
	v_sub_f32_e32 v12, v12, v13
	v_xor_b32_e32 v12, 0x80000000, v12
	s_nop 1
	v_add_f32_dpp v12, v12, v12 row_shr:1 row_mask:0xf bank_mask:0xf bound_ctrl:0
	s_nop 1
	v_add_f32_dpp v12, v12, v12 row_shr:2 row_mask:0xf bank_mask:0xf bound_ctrl:0
	s_nop 1
	v_add_f32_dpp v12, v12, v12 row_shr:4 row_mask:0xf bank_mask:0xf bound_ctrl:0
	s_nop 1
	v_add_f32_dpp v12, v12, v12 row_shr:8 row_mask:0xf bank_mask:0xf bound_ctrl:0
	s_nop 1
	v_add_f32_dpp v12, v12, v12 row_bcast:15 row_mask:0xa bank_mask:0xf
	s_nop 1
	v_add_f32_dpp v12, v12, v12 row_bcast:31 row_mask:0xc bank_mask:0xf
	v_sub_f32_e32 v15, v238, v12
	s_nop 0
	v_readlane_b32 s4, v12, 63
	v_mov_b32_e32 v14, v15
	s_nop 1
	v_sub_f32_e32 v16, s4, v12
	v_add_f32_e32 v16, v238, v16
	global_store_dword v[2:3], v12, off
	global_store_dword v[2:3], v15, off offset:1024
	v_max_f32_dpp v14, v14, v14 row_shr:1 row_mask:0xf bank_mask:0xf
	v_max_f32_dpp v16, v16, v16 row_shr:1 row_mask:0xf bank_mask:0xf
	s_nop 0
	v_max_f32_dpp v14, v14, v14 row_shr:2 row_mask:0xf bank_mask:0xf
	v_max_f32_dpp v16, v16, v16 row_shr:2 row_mask:0xf bank_mask:0xf
	s_nop 0
	v_max_f32_dpp v14, v14, v14 row_shr:4 row_mask:0xf bank_mask:0xf
	v_max_f32_dpp v16, v16, v16 row_shr:4 row_mask:0xf bank_mask:0xf
	s_nop 0
	v_max_f32_dpp v14, v14, v14 row_shr:8 row_mask:0xf bank_mask:0xf
	v_max_f32_dpp v16, v16, v16 row_shr:8 row_mask:0xf bank_mask:0xf
	s_nop 0
	v_max_f32_dpp v14, v14, v14 row_bcast:15 row_mask:0xa bank_mask:0xf
	v_max_f32_dpp v16, v16, v16 row_bcast:15 row_mask:0xa bank_mask:0xf
	s_nop 0
	v_max_f32_dpp v14, v14, v14 row_bcast:31 row_mask:0xc bank_mask:0xf
	v_max_f32_dpp v16, v16, v16 row_bcast:31 row_mask:0xc bank_mask:0xf
	s_nop 0
	v_writelane_b32 v206, s4, 7
	v_readlane_b32 s20, v16, 63
	global_store_dword v[2:3], v14, off offset:256
	v_lshl_add_u64 v[2:3], v[2:3], 0, s[30:31]
	v_writelane_b32 v207, s20, 7
	s_waitcnt vmcnt(38)
	v_mul_f32_e32 v12, 0xbfb8aa3b, v241
	v_exp_f32_e32 v12, v12
	s_nop 0
	v_add_f32_e32 v12, 1.0, v12
	v_cmp_gt_f32_e32 vcc, s39, v12
	s_nop 1
	v_cndmask_b32_e64 v13, 0, 32, vcc
	v_ldexp_f32 v12, v12, v13
	v_log_f32_e32 v12, v12
	v_cndmask_b32_e32 v13, 0, v213, vcc
	v_mul_f32_e32 v14, 0x3f317217, v12
	v_fma_f32 v14, v12, s0, -v14
	v_fmac_f32_e32 v14, 0x3377d1cf, v12
	v_fmac_f32_e32 v14, 0x3f317217, v12
	v_cmp_lt_f32_e64 vcc, |v12|, s1
	s_nop 1
	v_cndmask_b32_e32 v12, v12, v14, vcc
	v_sub_f32_e32 v12, v12, v13
	v_xor_b32_e32 v12, 0x80000000, v12
	s_nop 1
	v_add_f32_dpp v12, v12, v12 row_shr:1 row_mask:0xf bank_mask:0xf bound_ctrl:0
	s_nop 1
	v_add_f32_dpp v12, v12, v12 row_shr:2 row_mask:0xf bank_mask:0xf bound_ctrl:0
	s_nop 1
	v_add_f32_dpp v12, v12, v12 row_shr:4 row_mask:0xf bank_mask:0xf bound_ctrl:0
	s_nop 1
	v_add_f32_dpp v12, v12, v12 row_shr:8 row_mask:0xf bank_mask:0xf bound_ctrl:0
	s_nop 1
	v_add_f32_dpp v12, v12, v12 row_bcast:15 row_mask:0xa bank_mask:0xf
	s_nop 1
	v_add_f32_dpp v12, v12, v12 row_bcast:31 row_mask:0xc bank_mask:0xf
	v_sub_f32_e32 v15, v240, v12
	s_nop 0
	v_readlane_b32 s4, v12, 63
	v_mov_b32_e32 v14, v15
	s_nop 1
	v_sub_f32_e32 v16, s4, v12
	v_add_f32_e32 v16, v240, v16
	global_store_dword v[2:3], v12, off
	global_store_dword v[2:3], v15, off offset:1024
	v_max_f32_dpp v14, v14, v14 row_shr:1 row_mask:0xf bank_mask:0xf
	v_max_f32_dpp v16, v16, v16 row_shr:1 row_mask:0xf bank_mask:0xf
	s_nop 0
	v_max_f32_dpp v14, v14, v14 row_shr:2 row_mask:0xf bank_mask:0xf
	v_max_f32_dpp v16, v16, v16 row_shr:2 row_mask:0xf bank_mask:0xf
	s_nop 0
	v_max_f32_dpp v14, v14, v14 row_shr:4 row_mask:0xf bank_mask:0xf
	v_max_f32_dpp v16, v16, v16 row_shr:4 row_mask:0xf bank_mask:0xf
	s_nop 0
	v_max_f32_dpp v14, v14, v14 row_shr:8 row_mask:0xf bank_mask:0xf
	v_max_f32_dpp v16, v16, v16 row_shr:8 row_mask:0xf bank_mask:0xf
	s_nop 0
	v_max_f32_dpp v14, v14, v14 row_bcast:15 row_mask:0xa bank_mask:0xf
	v_max_f32_dpp v16, v16, v16 row_bcast:15 row_mask:0xa bank_mask:0xf
	s_nop 0
	v_max_f32_dpp v14, v14, v14 row_bcast:31 row_mask:0xc bank_mask:0xf
	v_max_f32_dpp v16, v16, v16 row_bcast:31 row_mask:0xc bank_mask:0xf
	s_nop 0
	v_writelane_b32 v206, s4, 8
	v_readlane_b32 s20, v16, 63
	global_store_dword v[2:3], v14, off offset:256
	v_lshl_add_u64 v[2:3], v[2:3], 0, s[30:31]
	v_writelane_b32 v207, s20, 8
	s_waitcnt vmcnt(39)
	v_mul_f32_e32 v12, 0xbfb8aa3b, v243
	v_exp_f32_e32 v12, v12
	s_nop 0
	v_add_f32_e32 v12, 1.0, v12
	v_cmp_gt_f32_e32 vcc, s39, v12
	s_nop 1
	v_cndmask_b32_e64 v13, 0, 32, vcc
	v_ldexp_f32 v12, v12, v13
	v_log_f32_e32 v12, v12
	v_cndmask_b32_e32 v13, 0, v213, vcc
	v_mul_f32_e32 v14, 0x3f317217, v12
	v_fma_f32 v14, v12, s0, -v14
	v_fmac_f32_e32 v14, 0x3377d1cf, v12
	v_fmac_f32_e32 v14, 0x3f317217, v12
	v_cmp_lt_f32_e64 vcc, |v12|, s1
	s_nop 1
	v_cndmask_b32_e32 v12, v12, v14, vcc
	v_sub_f32_e32 v12, v12, v13
	v_xor_b32_e32 v12, 0x80000000, v12
	s_nop 1
	v_add_f32_dpp v12, v12, v12 row_shr:1 row_mask:0xf bank_mask:0xf bound_ctrl:0
	s_nop 1
	v_add_f32_dpp v12, v12, v12 row_shr:2 row_mask:0xf bank_mask:0xf bound_ctrl:0
	s_nop 1
	v_add_f32_dpp v12, v12, v12 row_shr:4 row_mask:0xf bank_mask:0xf bound_ctrl:0
	s_nop 1
	v_add_f32_dpp v12, v12, v12 row_shr:8 row_mask:0xf bank_mask:0xf bound_ctrl:0
	s_nop 1
	v_add_f32_dpp v12, v12, v12 row_bcast:15 row_mask:0xa bank_mask:0xf
	s_nop 1
	v_add_f32_dpp v12, v12, v12 row_bcast:31 row_mask:0xc bank_mask:0xf
	v_sub_f32_e32 v15, v242, v12
	s_nop 0
	v_readlane_b32 s4, v12, 63
	v_mov_b32_e32 v14, v15
	s_nop 1
	v_sub_f32_e32 v16, s4, v12
	v_add_f32_e32 v16, v242, v16
	global_store_dword v[2:3], v12, off
	global_store_dword v[2:3], v15, off offset:1024
	v_max_f32_dpp v14, v14, v14 row_shr:1 row_mask:0xf bank_mask:0xf
	v_max_f32_dpp v16, v16, v16 row_shr:1 row_mask:0xf bank_mask:0xf
	s_nop 0
	v_max_f32_dpp v14, v14, v14 row_shr:2 row_mask:0xf bank_mask:0xf
	v_max_f32_dpp v16, v16, v16 row_shr:2 row_mask:0xf bank_mask:0xf
	s_nop 0
	v_max_f32_dpp v14, v14, v14 row_shr:4 row_mask:0xf bank_mask:0xf
	v_max_f32_dpp v16, v16, v16 row_shr:4 row_mask:0xf bank_mask:0xf
	s_nop 0
	v_max_f32_dpp v14, v14, v14 row_shr:8 row_mask:0xf bank_mask:0xf
	v_max_f32_dpp v16, v16, v16 row_shr:8 row_mask:0xf bank_mask:0xf
	s_nop 0
	v_max_f32_dpp v14, v14, v14 row_bcast:15 row_mask:0xa bank_mask:0xf
	v_max_f32_dpp v16, v16, v16 row_bcast:15 row_mask:0xa bank_mask:0xf
	s_nop 0
	v_max_f32_dpp v14, v14, v14 row_bcast:31 row_mask:0xc bank_mask:0xf
	v_max_f32_dpp v16, v16, v16 row_bcast:31 row_mask:0xc bank_mask:0xf
	s_nop 0
	v_writelane_b32 v206, s4, 9
	v_readlane_b32 s20, v16, 63
	global_store_dword v[2:3], v14, off offset:256
	v_lshl_add_u64 v[2:3], v[2:3], 0, s[30:31]
	v_writelane_b32 v207, s20, 9
	s_waitcnt vmcnt(40)
	v_mul_f32_e32 v12, 0xbfb8aa3b, v245
	v_exp_f32_e32 v12, v12
	s_nop 0
	v_add_f32_e32 v12, 1.0, v12
	v_cmp_gt_f32_e32 vcc, s39, v12
	s_nop 1
	v_cndmask_b32_e64 v13, 0, 32, vcc
	v_ldexp_f32 v12, v12, v13
	v_log_f32_e32 v12, v12
	v_cndmask_b32_e32 v13, 0, v213, vcc
	v_mul_f32_e32 v14, 0x3f317217, v12
	v_fma_f32 v14, v12, s0, -v14
	v_fmac_f32_e32 v14, 0x3377d1cf, v12
	v_fmac_f32_e32 v14, 0x3f317217, v12
	v_cmp_lt_f32_e64 vcc, |v12|, s1
	s_nop 1
	v_cndmask_b32_e32 v12, v12, v14, vcc
	v_sub_f32_e32 v12, v12, v13
	v_xor_b32_e32 v12, 0x80000000, v12
	s_nop 1
	v_add_f32_dpp v12, v12, v12 row_shr:1 row_mask:0xf bank_mask:0xf bound_ctrl:0
	s_nop 1
	v_add_f32_dpp v12, v12, v12 row_shr:2 row_mask:0xf bank_mask:0xf bound_ctrl:0
	s_nop 1
	v_add_f32_dpp v12, v12, v12 row_shr:4 row_mask:0xf bank_mask:0xf bound_ctrl:0
	s_nop 1
	v_add_f32_dpp v12, v12, v12 row_shr:8 row_mask:0xf bank_mask:0xf bound_ctrl:0
	s_nop 1
	v_add_f32_dpp v12, v12, v12 row_bcast:15 row_mask:0xa bank_mask:0xf
	s_nop 1
	v_add_f32_dpp v12, v12, v12 row_bcast:31 row_mask:0xc bank_mask:0xf
	v_sub_f32_e32 v15, v244, v12
	s_nop 0
	v_readlane_b32 s4, v12, 63
	v_mov_b32_e32 v14, v15
	s_nop 1
	v_sub_f32_e32 v16, s4, v12
	v_add_f32_e32 v16, v244, v16
	global_store_dword v[2:3], v12, off
	global_store_dword v[2:3], v15, off offset:1024
	v_max_f32_dpp v14, v14, v14 row_shr:1 row_mask:0xf bank_mask:0xf
	v_max_f32_dpp v16, v16, v16 row_shr:1 row_mask:0xf bank_mask:0xf
	s_nop 0
	v_max_f32_dpp v14, v14, v14 row_shr:2 row_mask:0xf bank_mask:0xf
	v_max_f32_dpp v16, v16, v16 row_shr:2 row_mask:0xf bank_mask:0xf
	s_nop 0
	v_max_f32_dpp v14, v14, v14 row_shr:4 row_mask:0xf bank_mask:0xf
	v_max_f32_dpp v16, v16, v16 row_shr:4 row_mask:0xf bank_mask:0xf
	s_nop 0
	v_max_f32_dpp v14, v14, v14 row_shr:8 row_mask:0xf bank_mask:0xf
	v_max_f32_dpp v16, v16, v16 row_shr:8 row_mask:0xf bank_mask:0xf
	s_nop 0
	v_max_f32_dpp v14, v14, v14 row_bcast:15 row_mask:0xa bank_mask:0xf
	v_max_f32_dpp v16, v16, v16 row_bcast:15 row_mask:0xa bank_mask:0xf
	s_nop 0
	v_max_f32_dpp v14, v14, v14 row_bcast:31 row_mask:0xc bank_mask:0xf
	v_max_f32_dpp v16, v16, v16 row_bcast:31 row_mask:0xc bank_mask:0xf
	s_nop 0
	v_writelane_b32 v206, s4, 10
	v_readlane_b32 s20, v16, 63
	global_store_dword v[2:3], v14, off offset:256
	v_lshl_add_u64 v[2:3], v[2:3], 0, s[30:31]
	v_writelane_b32 v207, s20, 10
	s_waitcnt vmcnt(41)
	v_mul_f32_e32 v12, 0xbfb8aa3b, v247
	v_exp_f32_e32 v12, v12
	s_nop 0
	v_add_f32_e32 v12, 1.0, v12
	v_cmp_gt_f32_e32 vcc, s39, v12
	s_nop 1
	v_cndmask_b32_e64 v13, 0, 32, vcc
	v_ldexp_f32 v12, v12, v13
	v_log_f32_e32 v12, v12
	v_cndmask_b32_e32 v13, 0, v213, vcc
	v_mul_f32_e32 v14, 0x3f317217, v12
	v_fma_f32 v14, v12, s0, -v14
	v_fmac_f32_e32 v14, 0x3377d1cf, v12
	v_fmac_f32_e32 v14, 0x3f317217, v12
	v_cmp_lt_f32_e64 vcc, |v12|, s1
	s_nop 1
	v_cndmask_b32_e32 v12, v12, v14, vcc
	v_sub_f32_e32 v12, v12, v13
	v_xor_b32_e32 v12, 0x80000000, v12
	s_nop 1
	v_add_f32_dpp v12, v12, v12 row_shr:1 row_mask:0xf bank_mask:0xf bound_ctrl:0
	s_nop 1
	v_add_f32_dpp v12, v12, v12 row_shr:2 row_mask:0xf bank_mask:0xf bound_ctrl:0
	s_nop 1
	v_add_f32_dpp v12, v12, v12 row_shr:4 row_mask:0xf bank_mask:0xf bound_ctrl:0
	s_nop 1
	v_add_f32_dpp v12, v12, v12 row_shr:8 row_mask:0xf bank_mask:0xf bound_ctrl:0
	s_nop 1
	v_add_f32_dpp v12, v12, v12 row_bcast:15 row_mask:0xa bank_mask:0xf
	s_nop 1
	v_add_f32_dpp v12, v12, v12 row_bcast:31 row_mask:0xc bank_mask:0xf
	v_sub_f32_e32 v15, v246, v12
	s_nop 0
	v_readlane_b32 s4, v12, 63
	v_mov_b32_e32 v14, v15
	s_nop 1
	v_sub_f32_e32 v16, s4, v12
	v_add_f32_e32 v16, v246, v16
	global_store_dword v[2:3], v12, off
	global_store_dword v[2:3], v15, off offset:1024
	v_max_f32_dpp v14, v14, v14 row_shr:1 row_mask:0xf bank_mask:0xf
	v_max_f32_dpp v16, v16, v16 row_shr:1 row_mask:0xf bank_mask:0xf
	s_nop 0
	v_max_f32_dpp v14, v14, v14 row_shr:2 row_mask:0xf bank_mask:0xf
	v_max_f32_dpp v16, v16, v16 row_shr:2 row_mask:0xf bank_mask:0xf
	s_nop 0
	v_max_f32_dpp v14, v14, v14 row_shr:4 row_mask:0xf bank_mask:0xf
	v_max_f32_dpp v16, v16, v16 row_shr:4 row_mask:0xf bank_mask:0xf
	s_nop 0
	v_max_f32_dpp v14, v14, v14 row_shr:8 row_mask:0xf bank_mask:0xf
	v_max_f32_dpp v16, v16, v16 row_shr:8 row_mask:0xf bank_mask:0xf
	s_nop 0
	v_max_f32_dpp v14, v14, v14 row_bcast:15 row_mask:0xa bank_mask:0xf
	v_max_f32_dpp v16, v16, v16 row_bcast:15 row_mask:0xa bank_mask:0xf
	s_nop 0
	v_max_f32_dpp v14, v14, v14 row_bcast:31 row_mask:0xc bank_mask:0xf
	v_max_f32_dpp v16, v16, v16 row_bcast:31 row_mask:0xc bank_mask:0xf
	s_nop 0
	v_writelane_b32 v206, s4, 11
	v_readlane_b32 s20, v16, 63
	global_store_dword v[2:3], v14, off offset:256
	v_lshl_add_u64 v[2:3], v[2:3], 0, s[30:31]
	v_writelane_b32 v207, s20, 11
	s_waitcnt vmcnt(42)
	v_mul_f32_e32 v12, 0xbfb8aa3b, v249
	v_exp_f32_e32 v12, v12
	s_nop 0
	v_add_f32_e32 v12, 1.0, v12
	v_cmp_gt_f32_e32 vcc, s39, v12
	s_nop 1
	v_cndmask_b32_e64 v13, 0, 32, vcc
	v_ldexp_f32 v12, v12, v13
	v_log_f32_e32 v12, v12
	v_cndmask_b32_e32 v13, 0, v213, vcc
	v_mul_f32_e32 v14, 0x3f317217, v12
	v_fma_f32 v14, v12, s0, -v14
	v_fmac_f32_e32 v14, 0x3377d1cf, v12
	v_fmac_f32_e32 v14, 0x3f317217, v12
	v_cmp_lt_f32_e64 vcc, |v12|, s1
	s_nop 1
	v_cndmask_b32_e32 v12, v12, v14, vcc
	v_sub_f32_e32 v12, v12, v13
	v_xor_b32_e32 v12, 0x80000000, v12
	s_nop 1
	v_add_f32_dpp v12, v12, v12 row_shr:1 row_mask:0xf bank_mask:0xf bound_ctrl:0
	s_nop 1
	v_add_f32_dpp v12, v12, v12 row_shr:2 row_mask:0xf bank_mask:0xf bound_ctrl:0
	s_nop 1
	v_add_f32_dpp v12, v12, v12 row_shr:4 row_mask:0xf bank_mask:0xf bound_ctrl:0
	s_nop 1
	v_add_f32_dpp v12, v12, v12 row_shr:8 row_mask:0xf bank_mask:0xf bound_ctrl:0
	s_nop 1
	v_add_f32_dpp v12, v12, v12 row_bcast:15 row_mask:0xa bank_mask:0xf
	s_nop 1
	v_add_f32_dpp v12, v12, v12 row_bcast:31 row_mask:0xc bank_mask:0xf
	v_sub_f32_e32 v15, v248, v12
	s_nop 0
	v_readlane_b32 s4, v12, 63
	v_mov_b32_e32 v14, v15
	s_nop 1
	v_sub_f32_e32 v16, s4, v12
	v_add_f32_e32 v16, v248, v16
	global_store_dword v[2:3], v12, off
	global_store_dword v[2:3], v15, off offset:1024
	v_max_f32_dpp v14, v14, v14 row_shr:1 row_mask:0xf bank_mask:0xf
	v_max_f32_dpp v16, v16, v16 row_shr:1 row_mask:0xf bank_mask:0xf
	s_nop 0
	v_max_f32_dpp v14, v14, v14 row_shr:2 row_mask:0xf bank_mask:0xf
	v_max_f32_dpp v16, v16, v16 row_shr:2 row_mask:0xf bank_mask:0xf
	s_nop 0
	v_max_f32_dpp v14, v14, v14 row_shr:4 row_mask:0xf bank_mask:0xf
	v_max_f32_dpp v16, v16, v16 row_shr:4 row_mask:0xf bank_mask:0xf
	s_nop 0
	v_max_f32_dpp v14, v14, v14 row_shr:8 row_mask:0xf bank_mask:0xf
	v_max_f32_dpp v16, v16, v16 row_shr:8 row_mask:0xf bank_mask:0xf
	s_nop 0
	v_max_f32_dpp v14, v14, v14 row_bcast:15 row_mask:0xa bank_mask:0xf
	v_max_f32_dpp v16, v16, v16 row_bcast:15 row_mask:0xa bank_mask:0xf
	s_nop 0
	v_max_f32_dpp v14, v14, v14 row_bcast:31 row_mask:0xc bank_mask:0xf
	v_max_f32_dpp v16, v16, v16 row_bcast:31 row_mask:0xc bank_mask:0xf
	s_nop 0
	v_writelane_b32 v206, s4, 12
	v_readlane_b32 s20, v16, 63
	global_store_dword v[2:3], v14, off offset:256
	v_lshl_add_u64 v[2:3], v[2:3], 0, s[30:31]
	v_writelane_b32 v207, s20, 12
	s_waitcnt vmcnt(43)
	v_mul_f32_e32 v12, 0xbfb8aa3b, v251
	v_exp_f32_e32 v12, v12
	s_nop 0
	v_add_f32_e32 v12, 1.0, v12
	v_cmp_gt_f32_e32 vcc, s39, v12
	s_nop 1
	v_cndmask_b32_e64 v13, 0, 32, vcc
	v_ldexp_f32 v12, v12, v13
	v_log_f32_e32 v12, v12
	v_cndmask_b32_e32 v13, 0, v213, vcc
	v_mul_f32_e32 v14, 0x3f317217, v12
	v_fma_f32 v14, v12, s0, -v14
	v_fmac_f32_e32 v14, 0x3377d1cf, v12
	v_fmac_f32_e32 v14, 0x3f317217, v12
	v_cmp_lt_f32_e64 vcc, |v12|, s1
	s_nop 1
	v_cndmask_b32_e32 v12, v12, v14, vcc
	v_sub_f32_e32 v12, v12, v13
	v_xor_b32_e32 v12, 0x80000000, v12
	s_nop 1
	v_add_f32_dpp v12, v12, v12 row_shr:1 row_mask:0xf bank_mask:0xf bound_ctrl:0
	s_nop 1
	v_add_f32_dpp v12, v12, v12 row_shr:2 row_mask:0xf bank_mask:0xf bound_ctrl:0
	s_nop 1
	v_add_f32_dpp v12, v12, v12 row_shr:4 row_mask:0xf bank_mask:0xf bound_ctrl:0
	s_nop 1
	v_add_f32_dpp v12, v12, v12 row_shr:8 row_mask:0xf bank_mask:0xf bound_ctrl:0
	s_nop 1
	v_add_f32_dpp v12, v12, v12 row_bcast:15 row_mask:0xa bank_mask:0xf
	s_nop 1
	v_add_f32_dpp v12, v12, v12 row_bcast:31 row_mask:0xc bank_mask:0xf
	v_sub_f32_e32 v15, v250, v12
	s_nop 0
	v_readlane_b32 s4, v12, 63
	v_mov_b32_e32 v14, v15
	s_nop 1
	v_sub_f32_e32 v16, s4, v12
	v_add_f32_e32 v16, v250, v16
	global_store_dword v[2:3], v12, off
	global_store_dword v[2:3], v15, off offset:1024
	v_max_f32_dpp v14, v14, v14 row_shr:1 row_mask:0xf bank_mask:0xf
	v_max_f32_dpp v16, v16, v16 row_shr:1 row_mask:0xf bank_mask:0xf
	s_nop 0
	v_max_f32_dpp v14, v14, v14 row_shr:2 row_mask:0xf bank_mask:0xf
	v_max_f32_dpp v16, v16, v16 row_shr:2 row_mask:0xf bank_mask:0xf
	s_nop 0
	v_max_f32_dpp v14, v14, v14 row_shr:4 row_mask:0xf bank_mask:0xf
	v_max_f32_dpp v16, v16, v16 row_shr:4 row_mask:0xf bank_mask:0xf
	s_nop 0
	v_max_f32_dpp v14, v14, v14 row_shr:8 row_mask:0xf bank_mask:0xf
	v_max_f32_dpp v16, v16, v16 row_shr:8 row_mask:0xf bank_mask:0xf
	s_nop 0
	v_max_f32_dpp v14, v14, v14 row_bcast:15 row_mask:0xa bank_mask:0xf
	v_max_f32_dpp v16, v16, v16 row_bcast:15 row_mask:0xa bank_mask:0xf
	s_nop 0
	v_max_f32_dpp v14, v14, v14 row_bcast:31 row_mask:0xc bank_mask:0xf
	v_max_f32_dpp v16, v16, v16 row_bcast:31 row_mask:0xc bank_mask:0xf
	s_nop 0
	v_writelane_b32 v206, s4, 13
	v_readlane_b32 s20, v16, 63
	global_store_dword v[2:3], v14, off offset:256
	v_lshl_add_u64 v[2:3], v[2:3], 0, s[30:31]
	v_writelane_b32 v207, s20, 13
	s_waitcnt vmcnt(44)
	v_mul_f32_e32 v12, 0xbfb8aa3b, v198
	v_exp_f32_e32 v12, v12
	s_nop 0
	v_add_f32_e32 v12, 1.0, v12
	v_cmp_gt_f32_e32 vcc, s39, v12
	s_nop 1
	v_cndmask_b32_e64 v13, 0, 32, vcc
	v_ldexp_f32 v12, v12, v13
	v_log_f32_e32 v12, v12
	v_cndmask_b32_e32 v13, 0, v213, vcc
	v_mul_f32_e32 v14, 0x3f317217, v12
	v_fma_f32 v14, v12, s0, -v14
	v_fmac_f32_e32 v14, 0x3377d1cf, v12
	v_fmac_f32_e32 v14, 0x3f317217, v12
	v_cmp_lt_f32_e64 vcc, |v12|, s1
	s_nop 1
	v_cndmask_b32_e32 v12, v12, v14, vcc
	v_sub_f32_e32 v12, v12, v13
	v_xor_b32_e32 v12, 0x80000000, v12
	s_nop 1
	v_add_f32_dpp v12, v12, v12 row_shr:1 row_mask:0xf bank_mask:0xf bound_ctrl:0
	s_nop 1
	v_add_f32_dpp v12, v12, v12 row_shr:2 row_mask:0xf bank_mask:0xf bound_ctrl:0
	s_nop 1
	v_add_f32_dpp v12, v12, v12 row_shr:4 row_mask:0xf bank_mask:0xf bound_ctrl:0
	s_nop 1
	v_add_f32_dpp v12, v12, v12 row_shr:8 row_mask:0xf bank_mask:0xf bound_ctrl:0
	s_nop 1
	v_add_f32_dpp v12, v12, v12 row_bcast:15 row_mask:0xa bank_mask:0xf
	s_nop 1
	v_add_f32_dpp v12, v12, v12 row_bcast:31 row_mask:0xc bank_mask:0xf
	v_sub_f32_e32 v15, v197, v12
	s_nop 0
	v_readlane_b32 s4, v12, 63
	v_mov_b32_e32 v14, v15
	s_nop 1
	v_sub_f32_e32 v16, s4, v12
	v_add_f32_e32 v16, v197, v16
	global_store_dword v[2:3], v12, off
	global_store_dword v[2:3], v15, off offset:1024
	v_max_f32_dpp v14, v14, v14 row_shr:1 row_mask:0xf bank_mask:0xf
	v_max_f32_dpp v16, v16, v16 row_shr:1 row_mask:0xf bank_mask:0xf
	s_nop 0
	v_max_f32_dpp v14, v14, v14 row_shr:2 row_mask:0xf bank_mask:0xf
	v_max_f32_dpp v16, v16, v16 row_shr:2 row_mask:0xf bank_mask:0xf
	s_nop 0
	v_max_f32_dpp v14, v14, v14 row_shr:4 row_mask:0xf bank_mask:0xf
	v_max_f32_dpp v16, v16, v16 row_shr:4 row_mask:0xf bank_mask:0xf
	s_nop 0
	v_max_f32_dpp v14, v14, v14 row_shr:8 row_mask:0xf bank_mask:0xf
	v_max_f32_dpp v16, v16, v16 row_shr:8 row_mask:0xf bank_mask:0xf
	s_nop 0
	v_max_f32_dpp v14, v14, v14 row_bcast:15 row_mask:0xa bank_mask:0xf
	v_max_f32_dpp v16, v16, v16 row_bcast:15 row_mask:0xa bank_mask:0xf
	s_nop 0
	v_max_f32_dpp v14, v14, v14 row_bcast:31 row_mask:0xc bank_mask:0xf
	v_max_f32_dpp v16, v16, v16 row_bcast:31 row_mask:0xc bank_mask:0xf
	s_nop 0
	v_writelane_b32 v206, s4, 14
	v_readlane_b32 s20, v16, 63
	global_store_dword v[2:3], v14, off offset:256
	v_lshl_add_u64 v[2:3], v[2:3], 0, s[30:31]
	v_writelane_b32 v207, s20, 14
	s_waitcnt vmcnt(45)
	v_mul_f32_e32 v12, 0xbfb8aa3b, v200
	v_exp_f32_e32 v12, v12
	s_nop 0
	v_add_f32_e32 v12, 1.0, v12
	v_cmp_gt_f32_e32 vcc, s39, v12
	s_nop 1
	v_cndmask_b32_e64 v13, 0, 32, vcc
	v_ldexp_f32 v12, v12, v13
	v_log_f32_e32 v12, v12
	v_cndmask_b32_e32 v13, 0, v213, vcc
	v_mul_f32_e32 v14, 0x3f317217, v12
	v_fma_f32 v14, v12, s0, -v14
	v_fmac_f32_e32 v14, 0x3377d1cf, v12
	v_fmac_f32_e32 v14, 0x3f317217, v12
	v_cmp_lt_f32_e64 vcc, |v12|, s1
	s_nop 1
	v_cndmask_b32_e32 v12, v12, v14, vcc
	v_sub_f32_e32 v12, v12, v13
	v_xor_b32_e32 v12, 0x80000000, v12
	s_nop 1
	v_add_f32_dpp v12, v12, v12 row_shr:1 row_mask:0xf bank_mask:0xf bound_ctrl:0
	s_nop 1
	v_add_f32_dpp v12, v12, v12 row_shr:2 row_mask:0xf bank_mask:0xf bound_ctrl:0
	s_nop 1
	v_add_f32_dpp v12, v12, v12 row_shr:4 row_mask:0xf bank_mask:0xf bound_ctrl:0
	s_nop 1
	v_add_f32_dpp v12, v12, v12 row_shr:8 row_mask:0xf bank_mask:0xf bound_ctrl:0
	s_nop 1
	v_add_f32_dpp v12, v12, v12 row_bcast:15 row_mask:0xa bank_mask:0xf
	s_nop 1
	v_add_f32_dpp v12, v12, v12 row_bcast:31 row_mask:0xc bank_mask:0xf
	v_sub_f32_e32 v15, v199, v12
	s_nop 0
	v_readlane_b32 s4, v12, 63
	v_mov_b32_e32 v14, v15
	s_nop 1
	v_sub_f32_e32 v16, s4, v12
	v_add_f32_e32 v16, v199, v16
	global_store_dword v[2:3], v12, off
	global_store_dword v[2:3], v15, off offset:1024
	v_max_f32_dpp v14, v14, v14 row_shr:1 row_mask:0xf bank_mask:0xf
	v_max_f32_dpp v16, v16, v16 row_shr:1 row_mask:0xf bank_mask:0xf
	s_nop 0
	v_max_f32_dpp v14, v14, v14 row_shr:2 row_mask:0xf bank_mask:0xf
	v_max_f32_dpp v16, v16, v16 row_shr:2 row_mask:0xf bank_mask:0xf
	s_nop 0
	v_max_f32_dpp v14, v14, v14 row_shr:4 row_mask:0xf bank_mask:0xf
	v_max_f32_dpp v16, v16, v16 row_shr:4 row_mask:0xf bank_mask:0xf
	s_nop 0
	v_max_f32_dpp v14, v14, v14 row_shr:8 row_mask:0xf bank_mask:0xf
	v_max_f32_dpp v16, v16, v16 row_shr:8 row_mask:0xf bank_mask:0xf
	s_nop 0
	v_max_f32_dpp v14, v14, v14 row_bcast:15 row_mask:0xa bank_mask:0xf
	v_max_f32_dpp v16, v16, v16 row_bcast:15 row_mask:0xa bank_mask:0xf
	s_nop 0
	v_max_f32_dpp v14, v14, v14 row_bcast:31 row_mask:0xc bank_mask:0xf
	v_max_f32_dpp v16, v16, v16 row_bcast:31 row_mask:0xc bank_mask:0xf
	s_nop 0
	v_writelane_b32 v206, s4, 15
	v_readlane_b32 s20, v16, 63
	global_store_dword v[2:3], v14, off offset:256
	v_lshl_add_u64 v[2:3], v[2:3], 0, s[30:31]
	v_writelane_b32 v207, s20, 15
	s_mov_b64 s[94:95], exec
	s_mov_b64 exec, 0xffff
	v_mbcnt_lo_u32_b32 v13, -1, 0
	v_lshlrev_b32_e32 v13, 5, v13
	v_add_u32_e32 v13, s17, v13
	v_add_u32_e32 v13, 0x14000, v13
	ds_write_b32 v13, v206
	ds_write_b32 v13, v207 offset:512
	s_mov_b64 exec, s[94:95]

.LBB0_575:
	s_or_b64 exec, exec, s[8:9]
	s_add_i32 s82, s82, 1
	s_cmp_ge_i32 s82, s83
	s_mov_b64 s[6:7], -1
	s_cbranch_scc1 .Lfar_23
	s_branch .LBB0_576
